# P3: RMS-gain loads only in a CU's first unit (head fixed, values stay in v205..v212); NA loop head: two wave-uniform tests by SALU instead of v_cndmask+v_cmp
# baseline (speedup 1.0000x reference)
; __device__ __forceinline__ void na_strip(const Params& P, LAS unsigned char* lds, int strip, int hsel, int tid, int lane, int wave) {
;     ...
;         const int lo = na_start(r, rows), lon = na_start(r + 2, rows);
;         const int nr0 = lo + 9, nr1 = lo + 10;
;         const bool need0 = (pi < npairs - 1) && (nr0 < lon + 9) && (nr0 < rows), need1 = (pi < npairs - 1) && (nr1 < lon + 9) && (nr1 < rows);
;         u32x4 nk0, nv0, nk1, nv1;
;         if (need0) { const size_t o = ((size_t)sq0 + (size_t)nr0 * 64) * 512 + ssrc; nk0 = *(const u32x4*)(KA + o); nv0 = *(const u32x4*)(VA + o); }
;         if (need1) { const size_t o = ((size_t)sq0 + (size_t)nr1 * 64) * 512 + ssrc; nk1 = *(const u32x4*)(KA + o); nv1 = *(const u32x4*)(VA + o); }
.LBB0_297:
	s_max_i32 s4, s76, 4
	s_add_i32 s4, s4, -4
	s_max_i32 s5, s76, 2
	s_min_u32 s6, s4, s77
	s_add_i32 s5, s5, -2
	s_min_u32 s7, s5, s77
	s_add_i32 s12, s6, 9
	s_cmp_lt_i32 s19, s18
	s_cselect_b64 s[16:17], -1, 0
	s_cmp_lt_u32 s4, s7
	s_cselect_b64 s[4:5], -1, 0
	s_cmp_lt_i32 s12, s75
	s_cselect_b64 s[14:15], -1, 0
	s_and_b64 s[14:15], s[16:17], s[14:15]
	s_and_b64 s[14:15], s[14:15], s[4:5]
	s_andn2_b64 s[4:5], exec, s[14:15]
	s_andn2_b64 vcc, exec, s[14:15]
	s_cbranch_vccnz .LBB0_299
	s_mov_b32 s13, s49
	s_lshl_b64 s[14:15], s[12:13], 15
	v_lshl_add_u64 v[2:3], s[14:15], 0, v[94:95]
	v_lshlrev_b64 v[2:3], 1, v[2:3]
	v_lshl_add_u64 v[6:7], s[46:47], 0, v[2:3]
	v_lshl_add_u64 v[2:3], s[44:45], 0, v[2:3]
	global_load_dwordx4 v[2:5], v[2:3], off
	s_nop 0
	global_load_dwordx4 v[6:9], v[6:7], off
.LBB0_299:
	s_add_i32 s14, s6, 10
	s_add_i32 s6, s6, 1
	s_cmp_lt_u32 s6, s7
	s_cselect_b64 s[6:7], -1, 0
	s_and_b64 s[6:7], s[16:17], s[6:7]
	s_cmp_lt_i32 s14, s75
	s_cselect_b64 s[26:27], -1, 0
	s_and_b64 s[26:27], s[6:7], s[26:27]
	s_andn2_b64 s[6:7], exec, s[26:27]
	s_andn2_b64 vcc, exec, s[26:27]
	s_cbranch_vccnz .LBB0_301
	s_mov_b32 s15, s49
	s_lshl_b64 s[26:27], s[14:15], 15
	v_lshl_add_u64 v[10:11], s[26:27], 0, v[94:95]
	v_lshlrev_b64 v[10:11], 1, v[10:11]
	v_lshl_add_u64 v[14:15], s[46:47], 0, v[10:11]
	v_lshl_add_u64 v[10:11], s[44:45], 0, v[10:11]
	global_load_dwordx4 v[10:13], v[10:11], off
	s_nop 0
	global_load_dwordx4 v[14:17], v[14:15], off

; #define LAS __attribute__((address_space(3)))
; __device__ __forceinline__ f32x4 mfma16(bf16x8 a, bf16x8 b, f32x4 c) { return __builtin_amdgcn_mfma_f32_16x16x32_bf16(a, b, c, 0, 0, 0); }
; #define LBAR() asm volatile("s_waitcnt lgkmcnt(0)\n\ts_barrier" ::: "memory")
; #define OPQ_ALL() do { asm volatile("" : "+v"(g), "+v"(l15), "+v"(q4), "+v"(p)); } while (0)
; __device__ __forceinline__ void ret_phase(const Params& P, LAS unsigned char* lds, int tid, int lane, int wave, int bid, int G) {
;     ...
;         const int gc = u >> 2, h = u & 3; const size_t tokc = (size_t)gc * 128;
;         const float lgf2 = -__expf(P.dec_f[h]) * LOG2E, lgb2 = -__expf(P.dec_b[h]) * LOG2E;
; #pragma unroll
;         for (int i = 0; i < 4; ++i) { const int idx = tid + 512 * i; const unsigned d = off256(idx >> 4, idx & 15);
;             *(LAS u32x4*)(Qt + d) = rq[i]; *(LAS u32x4*)(Kt + d) = rk[i]; *(LAS u32x4*)(Vt + d) = rv[i]; }
;         LBAR();
;         const bf16_t* Sf = ST + ((size_t)(gc * 4 + h) * 2 + 0) * 16384; const bf16_t* Sb = Sf + 16384;
;         u32x4 rsf[2], rsb[2];
; #pragma unroll
;         for (int j = 0; j < 2; ++j) { const int idx = tid + 512 * j; rsf[j] = *(const u32x4*)((const unsigned char*)Sf + 16 * idx); rsb[j] = *(const u32x4*)((const unsigned char*)Sb + 16 * idx); }
;         OPQ_ALL();
;         bf16x8 qf[4];
; #pragma unroll
;         for (int ks = 0; ks < 4; ++ks) qf[ks] = *(const LAS bf16x8*)(Qt + off256(w16 + l15, 4 * ks + g));
;         {
;             const int n = w16 + l15;
;             f32x4 sa[8];
; #pragma unroll
;             for (int mt = 0; mt < 8; ++mt) {
;                 f32x4 a = (f32x4){0.f, 0.f, 0.f, 0.f};
; #pragma unroll
;                 for (int ks = 0; ks < 4; ++ks) a = mfma16(*(const LAS bf16x8*)(Kt + off256(16 * mt + l15, 4 * ks + g)), qf[ks], a);
;                 sa[mt] = a; }
.Lp3_common:
	s_ashr_i32 s27, s26, 31
	s_lshl_b64 s[0:1], s[26:27], 16
	s_add_u32 s0, s44, s0
	s_addc_u32 s1, s45, s1
	v_lshl_add_u64 v[254:255], s[0:1], 0, v[116:117]
	global_load_dwordx4 v[68:71], v[254:255], off
	v_add_co_u32_e32 v52, vcc, s47, v254
	v_addc_co_u32_e32 v53, vcc, 0, v255, vcc
	global_load_dwordx4 v[76:79], v[52:53], off
	v_add_co_u32_e32 v52, vcc, s49, v254
	v_addc_co_u32_e32 v53, vcc, 0, v255, vcc
	global_load_dwordx4 v[84:87], v[52:53], off
	v_add_co_u32_e32 v52, vcc, s50, v254
	v_addc_co_u32_e32 v53, vcc, 0, v255, vcc
	global_load_dwordx4 v[92:95], v[52:53], off
	ds_write_b128 v50, v[6:9]
	ds_write_b128 v50, v[2:5] offset:32768
	ds_write_b128 v51, v[10:13]
	v_add_u32_e32 v51, 0, v109
	s_ashr_i32 s27, s26, 31
	s_ashr_i32 s40, s26, 2
	ds_write_b128 v51, v[14:17]
	ds_write_b128 v51, v[22:25] offset:32768
	v_add_u32_e32 v51, s48, v109
	s_lshl_b64 s[0:1], s[26:27], 16
	ds_write_b128 v51, v[18:21]
	ds_write_b128 v50, v[30:33] offset:16384
	ds_write_b128 v50, v[26:29] offset:49152
	ds_write_b128 v127, v[34:37]
	v_add_u32_e32 v50, 0, v111
	s_add_u32 s0, s44, s0
	ds_write_b128 v50, v[38:41]
	ds_write_b128 v50, v[46:49] offset:32768
	v_add_u32_e32 v50, s48, v111
	s_addc_u32 s1, s45, s1
	ds_write_b128 v50, v[42:45]
	s_waitcnt lgkmcnt(0)
	s_barrier
	s_mov_b64 vcc, s[84:85]
	s_cbranch_vccnz .Lp3_rgskip
	v_lshl_add_u32 v214, s57, 7, v1
	v_ashrrev_i32_e32 v215, 31, v214
	v_lshl_add_u64 v[214:215], v[214:215], 2, s[62:63]
	global_load_dword v205, v[214:215], off
	global_load_dword v206, v[214:215], off offset:64
	global_load_dword v207, v[214:215], off offset:128
	global_load_dword v208, v[214:215], off offset:192
	global_load_dword v209, v[214:215], off offset:256
	global_load_dword v210, v[214:215], off offset:320
	global_load_dword v211, v[214:215], off offset:384
	global_load_dword v212, v[214:215], off offset:448
.Lp3_rgskip:
	s_cmpk_lt_i32 s40, 0x200
	s_nop 0
	v_mul_f32_e32 v104, 0x3fb8aa3b, v104
	s_nop 0
	v_mul_f32_e32 v105, 0x3fb8aa3b, v105
	s_nop 0
	v_exp_f32_e32 v104, v104
	v_lshlrev_b32_e32 v50, 2, v1
	v_add_u32_e32 v119, s46, v1
	v_and_b32_e32 v66, 12, v50
	v_bfe_u32 v67, v1, 2, 2
	v_lshlrev_b32_e32 v135, 8, v119
	v_bitop3_b32 v50, v66, v118, v67 bitop3:0x36
	v_add_u32_e32 v52, 4, v118
	v_add_u32_e32 v100, 0, v135
	v_lshlrev_b32_e32 v50, 4, v50
	v_bitop3_b32 v52, v66, v52, v67 bitop3:0x36
	v_add_u32_e32 v51, v100, v50
	v_lshlrev_b32_e32 v72, 4, v52
	v_add_u32_e32 v52, v100, v72
	ds_read_b128 v[58:61], v51
	ds_read_b128 v[54:57], v52
	v_add_u32_e32 v51, 8, v118
	v_lshl_add_u32 v122, v1, 8, 0
	v_bitop3_b32 v51, v66, v51, v67 bitop3:0x36
	v_add_u32_e32 v156, v122, v50
	v_lshlrev_b32_e32 v80, 4, v51
	ds_read_b128 v[50:53], v156 offset:32768
	v_add_u32_e32 v157, v122, v72
	ds_read_b128 v[72:75], v157 offset:32768
	v_add_u32_e32 v62, v100, v80
	ds_read_b128 v[62:65], v62
	s_waitcnt lgkmcnt(2)
	v_mfma_f32_16x16x32_bf16 v[50:53], v[50:53], v[58:61], 0
	v_add_u32_e32 v158, v122, v80
	v_add_u32_e32 v96, 12, v118
	ds_read_b128 v[80:83], v158 offset:32768
	ds_read_b128 v[88:91], v156 offset:36864
	s_waitcnt lgkmcnt(3)
	v_mfma_f32_16x16x32_bf16 v[72:75], v[72:75], v[54:57], v[50:53]
	v_bitop3_b32 v96, v66, v96, v67 bitop3:0x36
	v_lshlrev_b32_e32 v123, 4, v96
	ds_read_b128 v[96:99], v157 offset:36864
	v_add_u32_e32 v50, v100, v123
	v_add_u32_e32 v159, v122, v123
	ds_read_b128 v[50:53], v50
	ds_read_b128 v[100:103], v158 offset:36864
	s_waitcnt lgkmcnt(4)
	v_mfma_f32_16x16x32_bf16 v[72:75], v[80:83], v[62:65], v[72:75]
	ds_read_b128 v[80:83], v159 offset:32768
	ds_read_b128 v[122:125], v159 offset:36864
	s_waitcnt lgkmcnt(1)
	v_mfma_f32_16x16x32_bf16 v[136:139], v[80:83], v[50:53], v[72:75]
	v_mfma_f32_16x16x32_bf16 v[72:75], v[88:91], v[58:61], 0
	v_mfma_f32_16x16x32_bf16 v[72:75], v[96:99], v[54:57], v[72:75]
	v_mfma_f32_16x16x32_bf16 v[72:75], v[100:103], v[62:65], v[72:75]
	s_waitcnt lgkmcnt(0)
	v_mfma_f32_16x16x32_bf16 v[122:125], v[122:125], v[50:53], v[72:75]
	s_nop 5
	ds_read_b128 v[72:75], v156 offset:40960
	ds_read_b128 v[80:83], v156 offset:45056
	ds_read_b128 v[88:91], v157 offset:40960
	ds_read_b128 v[96:99], v157 offset:45056
	s_waitcnt lgkmcnt(3)
	v_mfma_f32_16x16x32_bf16 v[72:75], v[72:75], v[58:61], 0
	s_waitcnt lgkmcnt(1)
	v_mfma_f32_16x16x32_bf16 v[72:75], v[88:91], v[54:57], v[72:75]
	ds_read_b128 v[88:91], v158 offset:40960
	ds_read_b128 v[100:103], v158 offset:45056
	s_waitcnt lgkmcnt(1)
	v_mfma_f32_16x16x32_bf16 v[72:75], v[88:91], v[62:65], v[72:75]
	ds_read_b128 v[88:91], v159 offset:40960
	ds_read_b128 v[140:143], v159 offset:45056
	s_waitcnt lgkmcnt(1)
	v_mfma_f32_16x16x32_bf16 v[144:147], v[88:91], v[50:53], v[72:75]
	v_mfma_f32_16x16x32_bf16 v[72:75], v[80:83], v[58:61], 0
	v_mfma_f32_16x16x32_bf16 v[72:75], v[96:99], v[54:57], v[72:75]
	v_mfma_f32_16x16x32_bf16 v[72:75], v[100:103], v[62:65], v[72:75]
	s_waitcnt lgkmcnt(0)
	v_mfma_f32_16x16x32_bf16 v[100:103], v[140:143], v[50:53], v[72:75]
	s_nop 5
	ds_read_b128 v[72:75], v156 offset:49152
	ds_read_b128 v[80:83], v156 offset:53248
	ds_read_b128 v[88:91], v157 offset:49152
	ds_read_b128 v[140:143], v157 offset:53248
	s_waitcnt lgkmcnt(3)
	v_mfma_f32_16x16x32_bf16 v[72:75], v[72:75], v[58:61], 0
	s_waitcnt lgkmcnt(1)
	v_mfma_f32_16x16x32_bf16 v[72:75], v[88:91], v[54:57], v[72:75]
	ds_read_b128 v[88:91], v158 offset:49152
	ds_read_b128 v[148:151], v158 offset:53248
	s_waitcnt lgkmcnt(1)
	v_mfma_f32_16x16x32_bf16 v[72:75], v[88:91], v[62:65], v[72:75]
	ds_read_b128 v[88:91], v159 offset:49152
	ds_read_b128 v[152:155], v159 offset:53248
	s_waitcnt lgkmcnt(1)
	v_mfma_f32_16x16x32_bf16 v[96:99], v[88:91], v[50:53], v[72:75]
	v_mfma_f32_16x16x32_bf16 v[72:75], v[80:83], v[58:61], 0
	v_mfma_f32_16x16x32_bf16 v[72:75], v[140:143], v[54:57], v[72:75]
	v_mfma_f32_16x16x32_bf16 v[72:75], v[148:151], v[62:65], v[72:75]
	s_waitcnt lgkmcnt(0)
	v_mfma_f32_16x16x32_bf16 v[88:91], v[152:155], v[50:53], v[72:75]
	s_nop 5
	ds_read_b128 v[72:75], v156 offset:57344
	ds_read_b128 v[140:143], v156 offset:61440
	ds_read_b128 v[80:83], v157 offset:57344
	ds_read_b128 v[148:151], v157 offset:61440
	s_waitcnt lgkmcnt(3)
	v_mfma_f32_16x16x32_bf16 v[72:75], v[72:75], v[58:61], 0
	s_waitcnt lgkmcnt(1)
	v_mfma_f32_16x16x32_bf16 v[72:75], v[80:83], v[54:57], v[72:75]
	ds_read_b128 v[80:83], v158 offset:57344
	ds_read_b128 v[152:155], v158 offset:61440
	s_waitcnt lgkmcnt(1)
	v_mfma_f32_16x16x32_bf16 v[72:75], v[80:83], v[62:65], v[72:75]
	ds_read_b128 v[80:83], v159 offset:57344
	ds_read_b128 v[156:159], v159 offset:61440
	s_waitcnt lgkmcnt(1)
	v_mfma_f32_16x16x32_bf16 v[80:83], v[80:83], v[50:53], v[72:75]
	v_mfma_f32_16x16x32_bf16 v[72:75], v[140:143], v[58:61], 0
	v_lshlrev_b32_e32 v142, 2, v118
	v_sub_u32_e32 v143, v119, v142
	v_exp_f32_e32 v140, v105
	v_mfma_f32_16x16x32_bf16 v[72:75], v[148:151], v[54:57], v[72:75]
	v_lshlrev_b32_e32 v141, 3, v118
	v_mul_f32_e32 v105, 0xbfb8aa3b, v104
	v_mul_f32_e32 v104, 0xbfb8aa3b, v140
	v_and_b32_e32 v141, 8, v141
	s_mov_b64 vcc, s[84:85]
	s_cbranch_vccnz .Lp3_maskdone
; __device__ __forceinline__ void ret_phase(const Params& P, LAS unsigned char* lds, int tid, int lane, int wave, int bid, int G) {
;     ...
;             for (int mt = 0; mt < 8; ++mt) {
;                 const f32x4 a = sa[mt];
;                 float e[4];
; #pragma unroll
;                 for (int i = 0; i < 4; ++i) { const int m = 16 * mt + 4 * g + i, df = n - m; const float f = __builtin_amdgcn_exp2f(df >= 0 ? lgf2 * (float)df : lgb2 * (float)(-df)); e[i] = a[i] * f; }
	v_subrev_u32_e32 v213, 0, v143
	v_sub_u32_e32 v218, 0, v143
	v_max_i32_e32 v218, v213, v218
	v_cvt_f32_u32_e32 v218, v218
	v_cmp_gt_i32_e32 vcc, 0, v213
	v_cndmask_b32_e32 v213, v105, v104, vcc
	v_mul_f32_e32 v213, v213, v218
	v_exp_f32_e32 v213, v213
	v_subrev_u32_e32 v219, 1, v143
	v_sub_u32_e32 v218, 1, v143
	v_max_i32_e32 v218, v219, v218
	v_cvt_f32_u32_e32 v218, v218
	v_cmp_gt_i32_e32 vcc, 0, v219
	v_cndmask_b32_e32 v219, v105, v104, vcc
	v_mul_f32_e32 v219, v219, v218
	v_exp_f32_e32 v219, v219
	v_subrev_u32_e32 v220, 2, v143
	v_sub_u32_e32 v218, 2, v143
	v_max_i32_e32 v218, v220, v218
	v_cvt_f32_u32_e32 v218, v218
	v_cmp_gt_i32_e32 vcc, 0, v220
	v_cndmask_b32_e32 v220, v105, v104, vcc
	v_mul_f32_e32 v220, v220, v218
	v_exp_f32_e32 v220, v220
	v_subrev_u32_e32 v221, 3, v143
	v_sub_u32_e32 v218, 3, v143
	v_max_i32_e32 v218, v221, v218
	v_cvt_f32_u32_e32 v218, v218
	v_cmp_gt_i32_e32 vcc, 0, v221
	v_cndmask_b32_e32 v221, v105, v104, vcc
	v_mul_f32_e32 v221, v221, v218
	v_exp_f32_e32 v221, v221
	v_subrev_u32_e32 v222, 16, v143
	v_sub_u32_e32 v218, 16, v143
	v_max_i32_e32 v218, v222, v218
	v_cvt_f32_u32_e32 v218, v218
	v_cmp_gt_i32_e32 vcc, 0, v222
	v_cndmask_b32_e32 v222, v105, v104, vcc
	v_mul_f32_e32 v222, v222, v218
	v_exp_f32_e32 v222, v222
	v_subrev_u32_e32 v223, 17, v143
	v_sub_u32_e32 v218, 17, v143
	v_max_i32_e32 v218, v223, v218
	v_cvt_f32_u32_e32 v218, v218
	v_cmp_gt_i32_e32 vcc, 0, v223
	v_cndmask_b32_e32 v223, v105, v104, vcc
	v_mul_f32_e32 v223, v223, v218
	v_exp_f32_e32 v223, v223
	v_subrev_u32_e32 v224, 18, v143
	v_sub_u32_e32 v218, 18, v143
	v_max_i32_e32 v218, v224, v218
	v_cvt_f32_u32_e32 v218, v218
	v_cmp_gt_i32_e32 vcc, 0, v224
	v_cndmask_b32_e32 v224, v105, v104, vcc
	v_mul_f32_e32 v224, v224, v218
	v_exp_f32_e32 v224, v224
	v_subrev_u32_e32 v225, 19, v143
	v_sub_u32_e32 v218, 19, v143
	v_max_i32_e32 v218, v225, v218
	v_cvt_f32_u32_e32 v218, v218
	v_cmp_gt_i32_e32 vcc, 0, v225
	v_cndmask_b32_e32 v225, v105, v104, vcc
	v_mul_f32_e32 v225, v225, v218
	v_exp_f32_e32 v225, v225
	v_subrev_u32_e32 v226, 32, v143
	v_sub_u32_e32 v218, 32, v143
	v_max_i32_e32 v218, v226, v218
	v_cvt_f32_u32_e32 v218, v218
	v_cmp_gt_i32_e32 vcc, 0, v226
	v_cndmask_b32_e32 v226, v105, v104, vcc
	v_mul_f32_e32 v226, v226, v218
	v_exp_f32_e32 v226, v226
	v_subrev_u32_e32 v227, 33, v143
	v_sub_u32_e32 v218, 33, v143
	v_max_i32_e32 v218, v227, v218
	v_cvt_f32_u32_e32 v218, v218
	v_cmp_gt_i32_e32 vcc, 0, v227
	v_cndmask_b32_e32 v227, v105, v104, vcc
	v_mul_f32_e32 v227, v227, v218
	v_exp_f32_e32 v227, v227
	v_subrev_u32_e32 v228, 34, v143
	v_sub_u32_e32 v218, 34, v143
	v_max_i32_e32 v218, v228, v218
	v_cvt_f32_u32_e32 v218, v218
	v_cmp_gt_i32_e32 vcc, 0, v228
	v_cndmask_b32_e32 v228, v105, v104, vcc
	v_mul_f32_e32 v228, v228, v218
	v_exp_f32_e32 v228, v228
	v_subrev_u32_e32 v229, 35, v143
	v_sub_u32_e32 v218, 35, v143
	v_max_i32_e32 v218, v229, v218
	v_cvt_f32_u32_e32 v218, v218
	v_cmp_gt_i32_e32 vcc, 0, v229
	v_cndmask_b32_e32 v229, v105, v104, vcc
	v_mul_f32_e32 v229, v229, v218
	v_exp_f32_e32 v229, v229
	v_subrev_u32_e32 v230, 48, v143
	v_sub_u32_e32 v218, 48, v143
	v_max_i32_e32 v218, v230, v218
	v_cvt_f32_u32_e32 v218, v218
	v_cmp_gt_i32_e32 vcc, 0, v230
	v_cndmask_b32_e32 v230, v105, v104, vcc
	v_mul_f32_e32 v230, v230, v218
	v_exp_f32_e32 v230, v230
	v_subrev_u32_e32 v231, 49, v143
	v_sub_u32_e32 v218, 49, v143
	v_max_i32_e32 v218, v231, v218
	v_cvt_f32_u32_e32 v218, v218
	v_cmp_gt_i32_e32 vcc, 0, v231
	v_cndmask_b32_e32 v231, v105, v104, vcc
	v_mul_f32_e32 v231, v231, v218
	v_exp_f32_e32 v231, v231
	v_subrev_u32_e32 v232, 50, v143
	v_sub_u32_e32 v218, 50, v143
	v_max_i32_e32 v218, v232, v218
	v_cvt_f32_u32_e32 v218, v218
	v_cmp_gt_i32_e32 vcc, 0, v232
	v_cndmask_b32_e32 v232, v105, v104, vcc
	v_mul_f32_e32 v232, v232, v218
	v_exp_f32_e32 v232, v232
	v_subrev_u32_e32 v233, 51, v143
	v_sub_u32_e32 v218, 51, v143
	v_max_i32_e32 v218, v233, v218
	v_cvt_f32_u32_e32 v218, v218
	v_cmp_gt_i32_e32 vcc, 0, v233
	v_cndmask_b32_e32 v233, v105, v104, vcc
	v_mul_f32_e32 v233, v233, v218
	v_exp_f32_e32 v233, v233
	v_subrev_u32_e32 v234, 64, v143
; __device__ __forceinline__ void ret_phase(const Params& P, LAS unsigned char* lds, int tid, int lane, int wave, int bid, int G) {
;     ...
;             for (int mt = 0; mt < 8; ++mt) {
;                 const f32x4 a = sa[mt];
;                 float e[4];
; #pragma unroll
;                 for (int i = 0; i < 4; ++i) { const int m = 16 * mt + 4 * g + i, df = n - m; const float f = __builtin_amdgcn_exp2f(df >= 0 ? lgf2 * (float)df : lgb2 * (float)(-df)); e[i] = a[i] * f; }
	v_sub_u32_e32 v218, 64, v143
	v_max_i32_e32 v218, v234, v218
	v_cvt_f32_u32_e32 v218, v218
	v_cmp_gt_i32_e32 vcc, 0, v234
	v_cndmask_b32_e32 v234, v105, v104, vcc
	v_mul_f32_e32 v234, v234, v218
	v_exp_f32_e32 v234, v234
	v_subrev_u32_e32 v235, 65, v143
	v_sub_u32_e32 v218, 65, v143
	v_max_i32_e32 v218, v235, v218
	v_cvt_f32_u32_e32 v218, v218
	v_cmp_gt_i32_e32 vcc, 0, v235
	v_cndmask_b32_e32 v235, v105, v104, vcc
	v_mul_f32_e32 v235, v235, v218
	v_exp_f32_e32 v235, v235
	v_subrev_u32_e32 v236, 66, v143
	v_sub_u32_e32 v218, 66, v143
	v_max_i32_e32 v218, v236, v218
	v_cvt_f32_u32_e32 v218, v218
	v_cmp_gt_i32_e32 vcc, 0, v236
	v_cndmask_b32_e32 v236, v105, v104, vcc
	v_mul_f32_e32 v236, v236, v218
	v_exp_f32_e32 v236, v236
	v_subrev_u32_e32 v237, 67, v143
	v_sub_u32_e32 v218, 67, v143
	v_max_i32_e32 v218, v237, v218
	v_cvt_f32_u32_e32 v218, v218
	v_cmp_gt_i32_e32 vcc, 0, v237
	v_cndmask_b32_e32 v237, v105, v104, vcc
	v_mul_f32_e32 v237, v237, v218
	v_exp_f32_e32 v237, v237
	v_subrev_u32_e32 v238, 80, v143
	v_sub_u32_e32 v218, 80, v143
	v_max_i32_e32 v218, v238, v218
	v_cvt_f32_u32_e32 v218, v218
	v_cmp_gt_i32_e32 vcc, 0, v238
	v_cndmask_b32_e32 v238, v105, v104, vcc
	v_mul_f32_e32 v238, v238, v218
	v_exp_f32_e32 v238, v238
	v_subrev_u32_e32 v239, 81, v143
	v_sub_u32_e32 v218, 81, v143
	v_max_i32_e32 v218, v239, v218
	v_cvt_f32_u32_e32 v218, v218
	v_cmp_gt_i32_e32 vcc, 0, v239
	v_cndmask_b32_e32 v239, v105, v104, vcc
	v_mul_f32_e32 v239, v239, v218
	v_exp_f32_e32 v239, v239
	v_subrev_u32_e32 v240, 82, v143
	v_sub_u32_e32 v218, 82, v143
	v_max_i32_e32 v218, v240, v218
	v_cvt_f32_u32_e32 v218, v218
	v_cmp_gt_i32_e32 vcc, 0, v240
	v_cndmask_b32_e32 v240, v105, v104, vcc
	v_mul_f32_e32 v240, v240, v218
	v_exp_f32_e32 v240, v240
	v_subrev_u32_e32 v241, 83, v143
	v_sub_u32_e32 v218, 83, v143
	v_max_i32_e32 v218, v241, v218
	v_cvt_f32_u32_e32 v218, v218
	v_cmp_gt_i32_e32 vcc, 0, v241
	v_cndmask_b32_e32 v241, v105, v104, vcc
	v_mul_f32_e32 v241, v241, v218
	v_exp_f32_e32 v241, v241
	v_subrev_u32_e32 v242, 96, v143
	v_sub_u32_e32 v218, 96, v143
	v_max_i32_e32 v218, v242, v218
	v_cvt_f32_u32_e32 v218, v218
	v_cmp_gt_i32_e32 vcc, 0, v242
	v_cndmask_b32_e32 v242, v105, v104, vcc
	v_mul_f32_e32 v242, v242, v218
	v_exp_f32_e32 v242, v242
	v_subrev_u32_e32 v243, 97, v143
	v_sub_u32_e32 v218, 97, v143
	v_max_i32_e32 v218, v243, v218
	v_cvt_f32_u32_e32 v218, v218
	v_cmp_gt_i32_e32 vcc, 0, v243
	v_cndmask_b32_e32 v243, v105, v104, vcc
	v_mul_f32_e32 v243, v243, v218
	v_exp_f32_e32 v243, v243
	v_subrev_u32_e32 v244, 98, v143
	v_sub_u32_e32 v218, 98, v143
	v_max_i32_e32 v218, v244, v218
	v_cvt_f32_u32_e32 v218, v218
	v_cmp_gt_i32_e32 vcc, 0, v244
	v_cndmask_b32_e32 v244, v105, v104, vcc
	v_mul_f32_e32 v244, v244, v218
	v_exp_f32_e32 v244, v244
	v_subrev_u32_e32 v245, 99, v143
	v_sub_u32_e32 v218, 99, v143
	v_max_i32_e32 v218, v245, v218
	v_cvt_f32_u32_e32 v218, v218
	v_cmp_gt_i32_e32 vcc, 0, v245
	v_cndmask_b32_e32 v245, v105, v104, vcc
	v_mul_f32_e32 v245, v245, v218
	v_exp_f32_e32 v245, v245
	v_subrev_u32_e32 v246, 112, v143
	v_sub_u32_e32 v218, 112, v143
	v_max_i32_e32 v218, v246, v218
	v_cvt_f32_u32_e32 v218, v218
	v_cmp_gt_i32_e32 vcc, 0, v246
	v_cndmask_b32_e32 v246, v105, v104, vcc
	v_mul_f32_e32 v246, v246, v218
	v_exp_f32_e32 v246, v246
	v_subrev_u32_e32 v247, 113, v143
	v_sub_u32_e32 v218, 113, v143
	v_max_i32_e32 v218, v247, v218
	v_cvt_f32_u32_e32 v218, v218
	v_cmp_gt_i32_e32 vcc, 0, v247
	v_cndmask_b32_e32 v247, v105, v104, vcc
	v_mul_f32_e32 v247, v247, v218
	v_exp_f32_e32 v247, v247
	v_subrev_u32_e32 v248, 114, v143
	v_sub_u32_e32 v218, 114, v143
	v_max_i32_e32 v218, v248, v218
	v_cvt_f32_u32_e32 v218, v218
	v_cmp_gt_i32_e32 vcc, 0, v248
	v_cndmask_b32_e32 v248, v105, v104, vcc
	v_mul_f32_e32 v248, v248, v218
	v_exp_f32_e32 v248, v248
	v_subrev_u32_e32 v249, 115, v143
	v_sub_u32_e32 v218, 115, v143
	v_max_i32_e32 v218, v249, v218
	v_cvt_f32_u32_e32 v218, v218
	v_cmp_gt_i32_e32 vcc, 0, v249
	v_cndmask_b32_e32 v249, v105, v104, vcc
	v_mul_f32_e32 v249, v249, v218
	v_exp_f32_e32 v249, v249
	s_mov_b64 s[84:85], s[86:87]
